# P2a conv: next iteration's 8 rows prefetched (scalar row base + per-lane offset) before the current iteration's arithmetic
# speedup vs baseline: 1.0001x; 1.0001x over previous
; __device__ __forceinline__ unsigned pk2(float lo, float hi) { f32x2_c v = {lo, hi}; return __builtin_bit_cast(unsigned, __builtin_convertvector(v, bf16x2_c)); }
; __device__ __forceinline__ float bf2f(unsigned short h) { return __uint_as_float(((unsigned)h) << 16); }
; __device__ __forceinline__ float silu_f(float x) { return x * __builtin_amdgcn_rcpf(1.f + __expf(-x)); }
; __device__ __forceinline__ void p2a_conv(const Args& A, int G) {
;     ...
;     for (int rb = blockIdx.x; rb < MROWS / 64; rb += G) {
;         const int m0 = rb * 64 + half * 32; const int tb = m0 & (SEQL - 1);
;         bf16x8 r0 = {}, r1 = {}, r2 = {};
;         if (tb > 0) { r0 = *(const bf16x8*)(P0 + (size_t)(m0 - 3) * LD0 + C0_XBC + ch); r1 = *(const bf16x8*)(P0 + (size_t)(m0 - 2) * LD0 + C0_XBC + ch); r2 = *(const bf16x8*)(P0 + (size_t)(m0 - 1) * LD0 + C0_XBC + ch); }
; #pragma unroll 1
;         for (int i0 = 0; i0 < 32; i0 += 8) { bf16x8 rr[8];
; #pragma unroll
;         for (int i = 0; i < 8; ++i) rr[i] = *(const bf16x8*)(P0 + (size_t)(m0 + i0 + i) * LD0 + C0_XBC + ch);
; #pragma unroll
;         for (int ii = 0; ii < 8; ++ii) { const int i = i0 + ii; const bf16x8 r3 = rr[ii]; float o[8];
; #pragma unroll
;             for (int e = 0; e < 8; ++e) { const float a = bs[e] + w[0][e] * bf2f((unsigned short)r0[e]) + w[1][e] * bf2f((unsigned short)r1[e]) + w[2][e] * bf2f((unsigned short)r2[e]) + w[3][e] * bf2f((unsigned short)r3[e]); o[e] = silu_f(a); }
;             v4u pw; pw.x = pk2(o[0], o[1]); pw.y = pk2(o[2], o[3]); pw.z = pk2(o[4], o[5]); pw.w = pk2(o[6], o[7]);
;             *(v4u*)(XC + (size_t)(m0 + i) * 2048 + ch) = pw; r0 = r1; r1 = r2; r2 = r3; } }
.LBB0_602:
	s_or_b64 exec, exec, s[10:11]
	v_readfirstlane_b32 s98, v125
	s_nop 0
	s_mul_hi_u32 s101, s98, s1
	s_mul_i32 s100, s98, s1
	s_add_u32 s100, s100, s8
	s_addc_u32 s101, s101, s9
	s_add_u32 s100, s100, 0x1000
	s_addc_u32 s101, s101, 0
	global_load_dwordx4 v[210:213], v58, s[100:101] offset:2048
	s_add_u32 s98, s100, 0x3400
	s_addc_u32 s99, s101, 0
	global_load_dwordx4 v[214:217], v58, s[98:99] offset:2048
	s_add_u32 s98, s100, 0x6800
	s_addc_u32 s99, s101, 0
	global_load_dwordx4 v[222:225], v58, s[98:99] offset:2048
	s_add_u32 s98, s100, 0x9c00
	s_addc_u32 s99, s101, 0
	global_load_dwordx4 v[226:229], v58, s[98:99] offset:2048
	s_add_u32 s98, s100, 0xd000
	s_addc_u32 s99, s101, 0
	global_load_dwordx4 v[230:233], v58, s[98:99] offset:2048
	s_add_u32 s98, s100, 0x10400
	s_addc_u32 s99, s101, 0
	global_load_dwordx4 v[234:237], v58, s[98:99] offset:2048
	s_add_u32 s98, s100, 0x13800
	s_addc_u32 s99, s101, 0
	global_load_dwordx4 v[238:241], v58, s[98:99] offset:2048
	s_add_u32 s98, s100, 0x16c00
	s_addc_u32 s99, s101, 0
	global_load_dwordx4 v[242:245], v58, s[98:99] offset:2048
	s_mov_b32 s4, -8
.LBB0_603:
	v_add_u32_e32 v41, s4, v125
	v_mov_b64_e32 v[60:61], s[8:9]
	s_waitcnt vmcnt(0) lgkmcnt(0)
	v_and_b32_e32 v67, 0xffff0000, v42
	v_lshlrev_b32_e32 v66, 16, v42
	v_and_b32_e32 v63, 0xffff0000, v50
	v_lshlrev_b32_e32 v62, 16, v50
	v_and_b32_e32 v71, 0xffff0000, v43
	v_lshlrev_b32_e32 v70, 16, v43
	v_and_b32_e32 v43, 0xffff0000, v51
	v_lshlrev_b32_e32 v42, 16, v51
	v_and_b32_e32 v51, 0xffff0000, v48
	v_lshlrev_b32_e32 v50, 16, v48
	v_and_b32_e32 v77, 0xffff0000, v45
	v_lshlrev_b32_e32 v76, 16, v45
	v_add_u32_e32 v48, 8, v41
	v_and_b32_e32 v65, 0xffff0000, v46
	v_lshlrev_b32_e32 v64, 16, v46
	v_and_b32_e32 v69, 0xffff0000, v47
	v_lshlrev_b32_e32 v68, 16, v47
	v_and_b32_e32 v73, 0xffff0000, v44
	v_lshlrev_b32_e32 v72, 16, v44
	v_and_b32_e32 v75, 0xffff0000, v49
	v_lshlrev_b32_e32 v74, 16, v49
	v_pk_fma_f32 v[66:67], v[0:1], v[66:67], v[32:33]
	v_pk_fma_f32 v[70:71], v[2:3], v[70:71], v[34:35]
	v_pk_fma_f32 v[76:77], v[6:7], v[76:77], v[38:39]
	v_mad_i64_i32 v[100:101], s[10:11], v48, s1, v[60:61]
	v_and_b32_e32 v47, 0xffff0000, v52
	v_lshlrev_b32_e32 v46, 16, v52
	v_add_u32_e32 v52, 9, v41
	v_add_u32_e32 v78, 10, v41
	v_pk_fma_f32 v[72:73], v[4:5], v[72:73], v[36:37]
	v_pk_fma_f32 v[90:91], v[0:1], v[64:65], v[32:33]
	v_pk_fma_f32 v[92:93], v[2:3], v[68:69], v[34:35]
	v_pk_fma_f32 v[64:65], v[8:9], v[64:65], v[66:67]
	v_pk_fma_f32 v[66:67], v[10:11], v[68:69], v[70:71]
	v_pk_fma_f32 v[68:69], v[14:15], v[74:75], v[76:77]
	v_lshl_add_u64 v[76:77], v[100:101], 0, v[58:59]
	v_pk_fma_f32 v[94:95], v[4:5], v[50:51], v[36:37]
	v_mad_i64_i32 v[102:103], s[10:11], v52, s1, v[60:61]
	v_ashrrev_i32_e32 v79, 31, v78
	v_pk_fma_f32 v[50:51], v[12:13], v[50:51], v[72:73]
	v_add_co_u32_e32 v76, vcc, 0x1000, v76
	v_add_u32_e32 v82, 12, v41
	v_pk_fma_f32 v[106:107], v[4:5], v[46:47], v[36:37]
	v_pk_fma_f32 v[120:121], v[10:11], v[42:43], v[92:93]
	v_pk_fma_f32 v[122:123], v[12:13], v[46:47], v[94:95]
	v_lshl_add_u64 v[92:93], v[102:103], 0, v[58:59]
	v_pk_fma_f32 v[134:135], v[20:21], v[46:47], v[50:51]
	v_lshlrev_b64 v[46:47], 12, v[78:79]
	v_addc_co_u32_e32 v77, vcc, 0, v77, vcc
	v_mad_i64_i32 v[108:109], s[10:11], v78, s1, v[60:61]
	v_ashrrev_i32_e32 v83, 31, v82
	v_lshl_add_u64 v[70:71], v[56:57], 0, v[46:47]
	v_add_co_u32_e32 v46, vcc, 0x1000, v92
	v_add_u32_e32 v80, 11, v41
	v_add_u32_e32 v84, 13, v41
	v_lshl_add_u64 v[94:95], v[108:109], 0, v[58:59]
	v_lshlrev_b64 v[50:51], 12, v[82:83]
	v_addc_co_u32_e32 v47, vcc, 0, v93, vcc
	v_and_b32_e32 v45, 0xffff0000, v53
	v_lshlrev_b32_e32 v44, 16, v53
	v_pk_fma_f32 v[96:97], v[6:7], v[74:75], v[38:39]
	v_ashrrev_i32_e32 v53, 31, v52
	v_mad_i64_i32 v[110:111], s[10:11], v80, s1, v[60:61]
	v_ashrrev_i32_e32 v85, 31, v84
	v_pk_fma_f32 v[132:133], v[18:19], v[42:43], v[66:67]
	v_lshl_add_u64 v[66:67], v[56:57], 0, v[50:51]
	v_add_co_u32_e32 v50, vcc, 0x1000, v94
	v_pk_fma_f32 v[112:113], v[6:7], v[44:45], v[38:39]
	v_pk_fma_f32 v[96:97], v[14:15], v[44:45], v[96:97]
	v_lshl_add_u64 v[100:101], v[110:111], 0, v[58:59]
	v_pk_fma_f32 v[136:137], v[22:23], v[44:45], v[68:69]
	v_lshlrev_b64 v[44:45], 12, v[52:53]
	v_lshlrev_b64 v[52:53], 12, v[84:85]
	v_addc_co_u32_e32 v51, vcc, 0, v95, vcc
	v_ashrrev_i32_e32 v49, 31, v48
	v_ashrrev_i32_e32 v81, 31, v80
	v_mad_i64_i32 v[114:115], s[10:11], v82, s1, v[60:61]
	v_pk_fma_f32 v[130:131], v[16:17], v[62:63], v[64:65]
	v_lshl_add_u64 v[64:65], v[56:57], 0, v[52:53]
	v_add_co_u32_e32 v52, vcc, 0x1000, v100
	v_pk_fma_f32 v[104:105], v[2:3], v[42:43], v[34:35]
	v_lshl_add_u64 v[108:109], v[114:115], 0, v[58:59]
	v_lshlrev_b64 v[42:43], 12, v[48:49]
	v_lshlrev_b64 v[48:49], 12, v[80:81]
	v_addc_co_u32_e32 v53, vcc, 0, v101, vcc
	v_mad_i64_i32 v[116:117], s[10:11], v84, s1, v[60:61]
	v_lshl_add_u64 v[74:75], v[56:57], 0, v[42:43]
	v_lshl_add_u64 v[72:73], v[56:57], 0, v[44:45]
	v_lshl_add_u64 v[68:69], v[56:57], 0, v[48:49]
	v_mov_b32_e32 v42, v210
	v_mov_b32_e32 v43, v211
	v_mov_b32_e32 v44, v212
	v_mov_b32_e32 v45, v213
	v_mov_b32_e32 v100, v226
	v_mov_b32_e32 v101, v227
	v_mov_b32_e32 v102, v228
	v_mov_b32_e32 v103, v229
	v_mov_b32_e32 v92, v222
	v_mov_b32_e32 v93, v223
	v_mov_b32_e32 v94, v224
	v_mov_b32_e32 v95, v225
	v_add_co_u32_e32 v50, vcc, 0x1000, v108
	v_mov_b32_e32 v46, v214
	v_mov_b32_e32 v47, v215
	v_mov_b32_e32 v48, v216
	v_mov_b32_e32 v49, v217
	v_add_u32_e32 v86, 14, v41
	v_lshl_add_u64 v[110:111], v[116:117], 0, v[58:59]
	v_addc_co_u32_e32 v51, vcc, 0, v109, vcc
	v_mad_i64_i32 v[118:119], s[10:11], v86, s1, v[60:61]
	v_add_co_u32_e32 v52, vcc, 0x1000, v110
	v_add_u32_e32 v88, 15, v41
	v_lshl_add_u64 v[114:115], v[118:119], 0, v[58:59]
	v_addc_co_u32_e32 v53, vcc, 0, v111, vcc
	v_ashrrev_i32_e32 v87, 31, v86
	v_ashrrev_i32_e32 v89, 31, v88
	v_mad_i64_i32 v[60:61], s[10:11], v88, s1, v[60:61]
	v_add_co_u32_e32 v76, vcc, 0x1000, v114
	v_lshl_add_u64 v[126:127], v[60:61], 0, v[58:59]
	v_lshlrev_b64 v[60:61], 12, v[86:87]
	v_lshlrev_b64 v[78:79], 12, v[88:89]
	v_mov_b32_e32 v108, v230
	v_mov_b32_e32 v109, v231
	v_mov_b32_e32 v110, v232
	v_mov_b32_e32 v111, v233
	v_mov_b32_e32 v116, v234
	v_mov_b32_e32 v117, v235
	v_mov_b32_e32 v118, v236
	v_mov_b32_e32 v119, v237
	v_addc_co_u32_e32 v77, vcc, 0, v115, vcc
	v_pk_fma_f32 v[98:99], v[0:1], v[62:63], v[32:33]
	v_pk_fma_f32 v[90:91], v[8:9], v[62:63], v[90:91]
	v_lshl_add_u64 v[62:63], v[56:57], 0, v[60:61]
	v_lshl_add_u64 v[60:61], v[56:57], 0, v[78:79]
	v_add_co_u32_e32 v78, vcc, 0x1000, v126
	s_add_i32 s4, s4, 8
	s_nop 0
	v_addc_co_u32_e32 v79, vcc, 0, v127, vcc
	v_mov_b32_e32 v126, v238
	v_mov_b32_e32 v127, v239
	v_mov_b32_e32 v128, v240
	v_mov_b32_e32 v129, v241
	v_mov_b32_e32 v50, v242
	v_mov_b32_e32 v51, v243
	v_mov_b32_e32 v52, v244
	v_mov_b32_e32 v53, v245
	s_cmp_gt_u32 s4, 23
	s_cbranch_scc1 .Lcv_nopf
; __device__ __forceinline__ float bf2f(unsigned short h) { return __uint_as_float(((unsigned)h) << 16); }
; __device__ __forceinline__ float silu_f(float x) { return x * __builtin_amdgcn_rcpf(1.f + __expf(-x)); }
; __device__ __forceinline__ void p2a_conv(const Args& A, int G) {
;     ...
;         for (int i0 = 0; i0 < 32; i0 += 8) { bf16x8 rr[8];
; #pragma unroll
;         for (int i = 0; i < 8; ++i) rr[i] = *(const bf16x8*)(P0 + (size_t)(m0 + i0 + i) * LD0 + C0_XBC + ch);
; #pragma unroll
;         for (int ii = 0; ii < 8; ++ii) { const int i = i0 + ii; const bf16x8 r3 = rr[ii]; float o[8];
; #pragma unroll
;             for (int e = 0; e < 8; ++e) { const float a = bs[e] + w[0][e] * bf2f((unsigned short)r0[e]) + w[1][e] * bf2f((unsigned short)r1[e]) + w[2][e] * bf2f((unsigned short)r2[e]) + w[3][e] * bf2f((unsigned short)r3[e]); o[e] = silu_f(a); }
	s_add_u32 s100, s100, 0x1a000
	s_addc_u32 s101, s101, 0
	global_load_dwordx4 v[210:213], v58, s[100:101] offset:2048
	s_add_u32 s98, s100, 0x3400
	s_addc_u32 s99, s101, 0
	global_load_dwordx4 v[214:217], v58, s[98:99] offset:2048
	s_add_u32 s98, s100, 0x6800
	s_addc_u32 s99, s101, 0
	global_load_dwordx4 v[222:225], v58, s[98:99] offset:2048
	s_add_u32 s98, s100, 0x9c00
	s_addc_u32 s99, s101, 0
	global_load_dwordx4 v[226:229], v58, s[98:99] offset:2048
	s_add_u32 s98, s100, 0xd000
	s_addc_u32 s99, s101, 0
	global_load_dwordx4 v[230:233], v58, s[98:99] offset:2048
	s_add_u32 s98, s100, 0x10400
	s_addc_u32 s99, s101, 0
	global_load_dwordx4 v[234:237], v58, s[98:99] offset:2048
	s_add_u32 s98, s100, 0x13800
	s_addc_u32 s99, s101, 0
	global_load_dwordx4 v[238:241], v58, s[98:99] offset:2048
	s_add_u32 s98, s100, 0x16c00
	s_addc_u32 s99, s101, 0
	global_load_dwordx4 v[242:245], v58, s[98:99] offset:2048
.Lcv_nopf:
	s_cmp_gt_u32 s4, 23
	s_waitcnt vmcnt(0) lgkmcnt(0)
	v_and_b32_e32 v85, 0xffff0000, v42
	v_lshlrev_b32_e32 v84, 16, v42
	v_and_b32_e32 v87, 0xffff0000, v43
	v_lshlrev_b32_e32 v86, 16, v43
	v_and_b32_e32 v43, 0xffff0000, v44
	v_lshlrev_b32_e32 v42, 16, v44
	v_and_b32_e32 v89, 0xffff0000, v45
	v_lshlrev_b32_e32 v88, 16, v45
	v_pk_fma_f32 v[76:77], v[24:25], v[84:85], v[130:131]
	v_pk_fma_f32 v[78:79], v[26:27], v[86:87], v[132:133]
	v_pk_fma_f32 v[80:81], v[28:29], v[42:43], v[134:135]
	v_pk_fma_f32 v[82:83], v[30:31], v[88:89], v[136:137]
	v_pk_fma_f32 v[44:45], v[16:17], v[84:85], v[90:91]
	v_and_b32_e32 v115, 0xffff0000, v46
	v_lshlrev_b32_e32 v114, 16, v46
	v_pk_fma_f32 v[90:91], v[18:19], v[86:87], v[120:121]
	v_and_b32_e32 v121, 0xffff0000, v47
	v_lshlrev_b32_e32 v120, 16, v47
	v_pk_fma_f32 v[46:47], v[20:21], v[42:43], v[122:123]
	v_and_b32_e32 v123, 0xffff0000, v48
	v_lshlrev_b32_e32 v122, 16, v48
	v_pk_fma_f32 v[96:97], v[22:23], v[88:89], v[96:97]
	v_and_b32_e32 v131, 0xffff0000, v49
	v_lshlrev_b32_e32 v130, 16, v49
	v_pk_fma_f32 v[48:49], v[8:9], v[84:85], v[98:99]
	v_pk_fma_f32 v[98:99], v[10:11], v[86:87], v[104:105]
	v_pk_fma_f32 v[104:105], v[12:13], v[42:43], v[106:107]
	v_pk_fma_f32 v[106:107], v[14:15], v[88:89], v[112:113]
	v_pk_fma_f32 v[112:113], v[0:1], v[84:85], v[32:33]
	v_pk_fma_f32 v[132:133], v[2:3], v[86:87], v[34:35]
	v_pk_fma_f32 v[42:43], v[4:5], v[42:43], v[36:37]
	v_pk_fma_f32 v[134:135], v[6:7], v[88:89], v[38:39]
	v_mul_f32_e32 v41, 0xbfb8aa3b, v76
	v_mul_f32_e32 v138, 0xbfb8aa3b, v77
	v_mul_f32_e32 v139, 0xbfb8aa3b, v78
	v_mul_f32_e32 v140, 0xbfb8aa3b, v79
	v_mul_f32_e32 v141, 0xbfb8aa3b, v80
	v_mul_f32_e32 v142, 0xbfb8aa3b, v81
	v_mul_f32_e32 v143, 0xbfb8aa3b, v82
	v_mul_f32_e32 v144, 0xbfb8aa3b, v83
	v_pk_fma_f32 v[84:85], v[24:25], v[114:115], v[44:45]
	v_pk_fma_f32 v[86:87], v[26:27], v[120:121], v[90:91]
	v_pk_fma_f32 v[88:89], v[28:29], v[122:123], v[46:47]
	v_pk_fma_f32 v[90:91], v[30:31], v[130:131], v[96:97]
	v_pk_fma_f32 v[44:45], v[16:17], v[114:115], v[48:49]
	v_and_b32_e32 v47, 0xffff0000, v92
	v_lshlrev_b32_e32 v46, 16, v92
	v_pk_fma_f32 v[48:49], v[18:19], v[120:121], v[98:99]
	v_and_b32_e32 v137, 0xffff0000, v93
	v_lshlrev_b32_e32 v136, 16, v93
	v_pk_fma_f32 v[96:97], v[20:21], v[122:123], v[104:105]
	v_and_b32_e32 v105, 0xffff0000, v94
	v_lshlrev_b32_e32 v104, 16, v94
	v_pk_fma_f32 v[98:99], v[22:23], v[130:131], v[106:107]
	v_and_b32_e32 v107, 0xffff0000, v95
	v_lshlrev_b32_e32 v106, 16, v95
	v_pk_fma_f32 v[112:113], v[8:9], v[114:115], v[112:113]
	v_pk_fma_f32 v[132:133], v[10:11], v[120:121], v[132:133]
	v_pk_fma_f32 v[42:43], v[12:13], v[122:123], v[42:43]
	v_pk_fma_f32 v[134:135], v[14:15], v[130:131], v[134:135]
	v_pk_fma_f32 v[114:115], v[0:1], v[114:115], v[32:33]
	v_pk_fma_f32 v[120:121], v[2:3], v[120:121], v[34:35]
	v_pk_fma_f32 v[122:123], v[4:5], v[122:123], v[36:37]
	v_pk_fma_f32 v[130:131], v[6:7], v[130:131], v[38:39]
	v_exp_f32_e32 v41, v41
	v_exp_f32_e32 v162, v138
	v_exp_f32_e32 v163, v139
	v_exp_f32_e32 v164, v140
	v_exp_f32_e32 v165, v141
	v_exp_f32_e32 v166, v142
	v_exp_f32_e32 v167, v143
	v_exp_f32_e32 v168, v144
	v_mul_f32_e32 v146, 0xbfb8aa3b, v84
	v_mul_f32_e32 v147, 0xbfb8aa3b, v85
	v_mul_f32_e32 v148, 0xbfb8aa3b, v86
	v_mul_f32_e32 v149, 0xbfb8aa3b, v87
	v_mul_f32_e32 v150, 0xbfb8aa3b, v88
	v_mul_f32_e32 v151, 0xbfb8aa3b, v89
	v_mul_f32_e32 v152, 0xbfb8aa3b, v90
	v_mul_f32_e32 v153, 0xbfb8aa3b, v91
	v_pk_fma_f32 v[92:93], v[24:25], v[46:47], v[44:45]
	v_pk_fma_f32 v[94:95], v[26:27], v[136:137], v[48:49]
	v_pk_fma_f32 v[96:97], v[28:29], v[104:105], v[96:97]
	v_pk_fma_f32 v[98:99], v[30:31], v[106:107], v[98:99]
	v_pk_fma_f32 v[44:45], v[16:17], v[46:47], v[112:113]
	v_and_b32_e32 v49, 0xffff0000, v100
	v_lshlrev_b32_e32 v48, 16, v100
	v_pk_fma_f32 v[112:113], v[18:19], v[136:137], v[132:133]
	v_and_b32_e32 v133, 0xffff0000, v101
	v_lshlrev_b32_e32 v132, 16, v101
	v_pk_fma_f32 v[42:43], v[20:21], v[104:105], v[42:43]
	v_and_b32_e32 v139, 0xffff0000, v102
	v_lshlrev_b32_e32 v138, 16, v102
	v_pk_fma_f32 v[134:135], v[22:23], v[106:107], v[134:135]
	v_and_b32_e32 v141, 0xffff0000, v103
	v_lshlrev_b32_e32 v140, 16, v103
	v_pk_fma_f32 v[114:115], v[8:9], v[46:47], v[114:115]
	v_pk_fma_f32 v[120:121], v[10:11], v[136:137], v[120:121]
	v_pk_fma_f32 v[122:123], v[12:13], v[104:105], v[122:123]
	v_pk_fma_f32 v[130:131], v[14:15], v[106:107], v[130:131]
	v_pk_fma_f32 v[46:47], v[0:1], v[46:47], v[32:33]
	v_pk_fma_f32 v[136:137], v[2:3], v[136:137], v[34:35]
	v_pk_fma_f32 v[142:143], v[4:5], v[104:105], v[36:37]
	v_pk_fma_f32 v[144:145], v[6:7], v[106:107], v[38:39]
	v_exp_f32_e32 v169, v146
	v_exp_f32_e32 v170, v147
	v_exp_f32_e32 v171, v148
	v_exp_f32_e32 v172, v149
; __device__ __forceinline__ float bf2f(unsigned short h) { return __uint_as_float(((unsigned)h) << 16); }
; __device__ __forceinline__ float silu_f(float x) { return x * __builtin_amdgcn_rcpf(1.f + __expf(-x)); }
; __device__ __forceinline__ void p2a_conv(const Args& A, int G) {
;     ...
;         for (int ii = 0; ii < 8; ++ii) { const int i = i0 + ii; const bf16x8 r3 = rr[ii]; float o[8];
; #pragma unroll
;             for (int e = 0; e < 8; ++e) { const float a = bs[e] + w[0][e] * bf2f((unsigned short)r0[e]) + w[1][e] * bf2f((unsigned short)r1[e]) + w[2][e] * bf2f((unsigned short)r2[e]) + w[3][e] * bf2f((unsigned short)r3[e]); o[e] = silu_f(a); }
	v_exp_f32_e32 v173, v150
	v_exp_f32_e32 v174, v151
	v_exp_f32_e32 v175, v152
	v_exp_f32_e32 v176, v153
	v_mul_f32_e32 v146, 0xbfb8aa3b, v92
	v_mul_f32_e32 v147, 0xbfb8aa3b, v93
	v_mul_f32_e32 v148, 0xbfb8aa3b, v94
	v_mul_f32_e32 v149, 0xbfb8aa3b, v95
	v_mul_f32_e32 v150, 0xbfb8aa3b, v96
	v_mul_f32_e32 v151, 0xbfb8aa3b, v97
	v_mul_f32_e32 v152, 0xbfb8aa3b, v98
	v_mul_f32_e32 v153, 0xbfb8aa3b, v99
	v_pk_fma_f32 v[100:101], v[24:25], v[48:49], v[44:45]
	v_pk_fma_f32 v[102:103], v[26:27], v[132:133], v[112:113]
	v_pk_fma_f32 v[104:105], v[28:29], v[138:139], v[42:43]
	v_pk_fma_f32 v[106:107], v[30:31], v[140:141], v[134:135]
	v_pk_fma_f32 v[42:43], v[16:17], v[48:49], v[114:115]
	v_and_b32_e32 v45, 0xffff0000, v108
	v_lshlrev_b32_e32 v44, 16, v108
	v_pk_fma_f32 v[112:113], v[18:19], v[132:133], v[120:121]
	v_and_b32_e32 v121, 0xffff0000, v109
	v_lshlrev_b32_e32 v120, 16, v109
	v_pk_fma_f32 v[114:115], v[20:21], v[138:139], v[122:123]
	v_and_b32_e32 v123, 0xffff0000, v110
	v_lshlrev_b32_e32 v122, 16, v110
	v_pk_fma_f32 v[130:131], v[22:23], v[140:141], v[130:131]
	v_and_b32_e32 v135, 0xffff0000, v111
	v_lshlrev_b32_e32 v134, 16, v111
	v_pk_fma_f32 v[46:47], v[8:9], v[48:49], v[46:47]
	v_pk_fma_f32 v[136:137], v[10:11], v[132:133], v[136:137]
	v_pk_fma_f32 v[142:143], v[12:13], v[138:139], v[142:143]
	v_pk_fma_f32 v[144:145], v[14:15], v[140:141], v[144:145]
	v_pk_fma_f32 v[48:49], v[0:1], v[48:49], v[32:33]
	v_pk_fma_f32 v[132:133], v[2:3], v[132:133], v[34:35]
	v_pk_fma_f32 v[138:139], v[4:5], v[138:139], v[36:37]
	v_pk_fma_f32 v[140:141], v[6:7], v[140:141], v[38:39]
	v_exp_f32_e32 v177, v146
	v_exp_f32_e32 v178, v147
	v_exp_f32_e32 v179, v148
	v_exp_f32_e32 v180, v149
	v_exp_f32_e32 v181, v150
	v_exp_f32_e32 v182, v151
	v_exp_f32_e32 v183, v152
	v_exp_f32_e32 v184, v153
	v_mul_f32_e32 v158, 0xbfb8aa3b, v100
	v_mul_f32_e32 v159, 0xbfb8aa3b, v101
	v_mul_f32_e32 v160, 0xbfb8aa3b, v102
	v_mul_f32_e32 v161, 0xbfb8aa3b, v103
	v_mul_f32_e32 v185, 0xbfb8aa3b, v104
	v_mul_f32_e32 v186, 0xbfb8aa3b, v105
	v_mul_f32_e32 v187, 0xbfb8aa3b, v106
	v_mul_f32_e32 v188, 0xbfb8aa3b, v107
	v_pk_fma_f32 v[108:109], v[24:25], v[44:45], v[42:43]
	v_pk_fma_f32 v[110:111], v[26:27], v[120:121], v[112:113]
	v_pk_fma_f32 v[112:113], v[28:29], v[122:123], v[114:115]
	v_pk_fma_f32 v[114:115], v[30:31], v[134:135], v[130:131]
	v_pk_fma_f32 v[46:47], v[16:17], v[44:45], v[46:47]
	v_and_b32_e32 v131, 0xffff0000, v116
	v_lshlrev_b32_e32 v130, 16, v116
	v_pk_fma_f32 v[136:137], v[18:19], v[120:121], v[136:137]
	v_and_b32_e32 v147, 0xffff0000, v117
	v_lshlrev_b32_e32 v146, 16, v117
	v_pk_fma_f32 v[142:143], v[20:21], v[122:123], v[142:143]
	v_and_b32_e32 v149, 0xffff0000, v118
	v_lshlrev_b32_e32 v148, 16, v118
	v_pk_fma_f32 v[144:145], v[22:23], v[134:135], v[144:145]
	v_and_b32_e32 v151, 0xffff0000, v119
	v_lshlrev_b32_e32 v150, 16, v119
	v_pk_fma_f32 v[48:49], v[8:9], v[44:45], v[48:49]
	v_pk_fma_f32 v[132:133], v[10:11], v[120:121], v[132:133]
	v_pk_fma_f32 v[138:139], v[12:13], v[122:123], v[138:139]
	v_pk_fma_f32 v[140:141], v[14:15], v[134:135], v[140:141]
	v_pk_fma_f32 v[152:153], v[0:1], v[44:45], v[32:33]
	v_pk_fma_f32 v[154:155], v[2:3], v[120:121], v[34:35]
	v_pk_fma_f32 v[156:157], v[4:5], v[122:123], v[36:37]
	v_pk_fma_f32 v[134:135], v[6:7], v[134:135], v[38:39]
	v_mov_b64_e32 v[42:43], v[116:117]
	v_mov_b64_e32 v[44:45], v[118:119]
	v_exp_f32_e32 v189, v158
	v_exp_f32_e32 v190, v159
	v_exp_f32_e32 v191, v160
	v_exp_f32_e32 v192, v161
	v_exp_f32_e32 v185, v185
	v_exp_f32_e32 v186, v186
	v_exp_f32_e32 v187, v187
	v_exp_f32_e32 v188, v188
	v_mul_f32_e32 v193, 0xbfb8aa3b, v108
	v_mul_f32_e32 v194, 0xbfb8aa3b, v109
	v_mul_f32_e32 v195, 0xbfb8aa3b, v110
	v_mul_f32_e32 v196, 0xbfb8aa3b, v111
	v_mul_f32_e32 v197, 0xbfb8aa3b, v112
	v_mul_f32_e32 v198, 0xbfb8aa3b, v113
	v_mul_f32_e32 v199, 0xbfb8aa3b, v114
	v_mul_f32_e32 v200, 0xbfb8aa3b, v115
	v_pk_fma_f32 v[116:117], v[24:25], v[130:131], v[46:47]
	v_pk_fma_f32 v[118:119], v[26:27], v[146:147], v[136:137]
	v_pk_fma_f32 v[120:121], v[28:29], v[148:149], v[142:143]
	v_pk_fma_f32 v[122:123], v[30:31], v[150:151], v[144:145]
	v_pk_fma_f32 v[136:137], v[16:17], v[130:131], v[48:49]
	v_and_b32_e32 v143, 0xffff0000, v126
	v_lshlrev_b32_e32 v142, 16, v126
	v_pk_fma_f32 v[132:133], v[18:19], v[146:147], v[132:133]
	v_and_b32_e32 v145, 0xffff0000, v127
	v_lshlrev_b32_e32 v144, 16, v127
	v_pk_fma_f32 v[138:139], v[20:21], v[148:149], v[138:139]
	v_and_b32_e32 v159, 0xffff0000, v128
	v_lshlrev_b32_e32 v158, 16, v128
	v_pk_fma_f32 v[140:141], v[22:23], v[150:151], v[140:141]
	v_and_b32_e32 v161, 0xffff0000, v129
	v_lshlrev_b32_e32 v160, 16, v129
	v_pk_fma_f32 v[130:131], v[8:9], v[130:131], v[152:153]
	v_pk_fma_f32 v[146:147], v[10:11], v[146:147], v[154:155]
	v_pk_fma_f32 v[148:149], v[12:13], v[148:149], v[156:157]
	v_pk_fma_f32 v[134:135], v[14:15], v[150:151], v[134:135]
	v_mov_b64_e32 v[46:47], v[126:127]
	v_mov_b64_e32 v[48:49], v[128:129]
	v_add_f32_e32 v41, 1.0, v41
	v_add_f32_e32 v151, 1.0, v162
	v_add_f32_e32 v152, 1.0, v163
	v_add_f32_e32 v153, 1.0, v164
	v_add_f32_e32 v154, 1.0, v165
	v_add_f32_e32 v155, 1.0, v166
	v_add_f32_e32 v156, 1.0, v167
	v_add_f32_e32 v157, 1.0, v168
	v_exp_f32_e32 v193, v193
	v_exp_f32_e32 v194, v194
	v_exp_f32_e32 v195, v195
	v_exp_f32_e32 v196, v196
	v_exp_f32_e32 v197, v197
	v_exp_f32_e32 v198, v198
	v_exp_f32_e32 v199, v199
	v_exp_f32_e32 v200, v200
	v_mul_f32_e32 v162, 0xbfb8aa3b, v116
	v_mul_f32_e32 v163, 0xbfb8aa3b, v117
	v_mul_f32_e32 v164, 0xbfb8aa3b, v118
	v_mul_f32_e32 v165, 0xbfb8aa3b, v119
	v_mul_f32_e32 v166, 0xbfb8aa3b, v120
	v_mul_f32_e32 v167, 0xbfb8aa3b, v121
; __device__ __forceinline__ float bf2f(unsigned short h) { return __uint_as_float(((unsigned)h) << 16); }
; __device__ __forceinline__ float silu_f(float x) { return x * __builtin_amdgcn_rcpf(1.f + __expf(-x)); }
; __device__ __forceinline__ void p2a_conv(const Args& A, int G) {
;     ...
;             for (int e = 0; e < 8; ++e) { const float a = bs[e] + w[0][e] * bf2f((unsigned short)r0[e]) + w[1][e] * bf2f((unsigned short)r1[e]) + w[2][e] * bf2f((unsigned short)r2[e]) + w[3][e] * bf2f((unsigned short)r3[e]); o[e] = silu_f(a); }
	v_mul_f32_e32 v168, 0xbfb8aa3b, v122
	v_mul_f32_e32 v201, 0xbfb8aa3b, v123
	v_pk_fma_f32 v[126:127], v[24:25], v[142:143], v[136:137]
	v_pk_fma_f32 v[128:129], v[26:27], v[144:145], v[132:133]
	v_pk_fma_f32 v[132:133], v[28:29], v[158:159], v[138:139]
	v_pk_fma_f32 v[136:137], v[30:31], v[160:161], v[140:141]
	v_pk_fma_f32 v[130:131], v[16:17], v[142:143], v[130:131]
	v_and_b32_e32 v139, 0xffff0000, v50
	v_lshlrev_b32_e32 v138, 16, v50
	v_pk_fma_f32 v[140:141], v[18:19], v[144:145], v[146:147]
	v_and_b32_e32 v143, 0xffff0000, v51
	v_lshlrev_b32_e32 v142, 16, v51
	v_pk_fma_f32 v[144:145], v[20:21], v[158:159], v[148:149]
	v_and_b32_e32 v147, 0xffff0000, v52
	v_lshlrev_b32_e32 v146, 16, v52
	v_pk_fma_f32 v[134:135], v[22:23], v[160:161], v[134:135]
	v_and_b32_e32 v149, 0xffff0000, v53
	v_lshlrev_b32_e32 v148, 16, v53
	v_rcp_f32_e32 v150, v41
	v_rcp_f32_e32 v151, v151
	v_rcp_f32_e32 v152, v152
	v_rcp_f32_e32 v153, v153
	v_rcp_f32_e32 v154, v154
	v_rcp_f32_e32 v155, v155
	v_rcp_f32_e32 v156, v156
	v_rcp_f32_e32 v157, v157
	v_add_f32_e32 v41, 1.0, v169
	v_add_f32_e32 v158, 1.0, v170
	v_add_f32_e32 v159, 1.0, v171
	v_add_f32_e32 v160, 1.0, v172
	v_add_f32_e32 v161, 1.0, v173
	v_add_f32_e32 v169, 1.0, v174
	v_add_f32_e32 v170, 1.0, v175
	v_add_f32_e32 v171, 1.0, v176
	v_exp_f32_e32 v174, v162
	v_exp_f32_e32 v175, v163
	v_exp_f32_e32 v176, v164
	v_exp_f32_e32 v202, v165
	v_exp_f32_e32 v203, v166
	v_exp_f32_e32 v204, v167
	v_exp_f32_e32 v205, v168
	v_exp_f32_e32 v201, v201
	v_mul_f32_e32 v162, 0xbfb8aa3b, v126
	v_mul_f32_e32 v163, 0xbfb8aa3b, v127
	v_mul_f32_e32 v164, 0xbfb8aa3b, v128
	v_mul_f32_e32 v165, 0xbfb8aa3b, v129
	v_mul_f32_e32 v166, 0xbfb8aa3b, v132
	v_mul_f32_e32 v167, 0xbfb8aa3b, v133
	v_mul_f32_e32 v168, 0xbfb8aa3b, v136
	v_mul_f32_e32 v172, 0xbfb8aa3b, v137
	v_pk_fma_f32 v[130:131], v[24:25], v[138:139], v[130:131]
	v_pk_fma_f32 v[138:139], v[26:27], v[142:143], v[140:141]
	v_pk_fma_f32 v[140:141], v[28:29], v[146:147], v[144:145]
	v_pk_fma_f32 v[134:135], v[30:31], v[148:149], v[134:135]
	v_rcp_f32_e32 v142, v41
	v_rcp_f32_e32 v143, v158
	v_rcp_f32_e32 v144, v159
	v_rcp_f32_e32 v145, v160
	v_rcp_f32_e32 v146, v161
	v_rcp_f32_e32 v147, v169
	v_rcp_f32_e32 v148, v170
	v_rcp_f32_e32 v149, v171
	v_add_f32_e32 v41, 1.0, v177
	v_add_f32_e32 v159, 1.0, v178
	v_add_f32_e32 v160, 1.0, v179
	v_add_f32_e32 v161, 1.0, v180
	v_add_f32_e32 v169, 1.0, v181
	v_add_f32_e32 v170, 1.0, v182
	v_add_f32_e32 v171, 1.0, v183
	v_add_f32_e32 v173, 1.0, v184
	v_exp_f32_e32 v177, v162
	v_exp_f32_e32 v178, v163
	v_exp_f32_e32 v179, v164
	v_exp_f32_e32 v180, v165
	v_exp_f32_e32 v181, v166
	v_exp_f32_e32 v182, v167
	v_exp_f32_e32 v183, v168
	v_exp_f32_e32 v184, v172
	v_mul_f32_e32 v166, 0xbfb8aa3b, v130
	v_mul_f32_e32 v167, 0xbfb8aa3b, v131
	v_mul_f32_e32 v168, 0xbfb8aa3b, v138
	v_mul_f32_e32 v172, 0xbfb8aa3b, v139
	v_mul_f32_e32 v206, 0xbfb8aa3b, v140
	v_mul_f32_e32 v207, 0xbfb8aa3b, v141
	v_mul_f32_e32 v208, 0xbfb8aa3b, v134
	v_mul_f32_e32 v209, 0xbfb8aa3b, v135
	v_rcp_f32_e32 v158, v41
	v_rcp_f32_e32 v159, v159
	v_rcp_f32_e32 v160, v160
	v_rcp_f32_e32 v161, v161
	v_rcp_f32_e32 v162, v169
	v_rcp_f32_e32 v163, v170
	v_rcp_f32_e32 v164, v171
	v_rcp_f32_e32 v165, v173
	v_add_f32_e32 v41, 1.0, v189
	v_add_f32_e32 v169, 1.0, v190
	v_add_f32_e32 v170, 1.0, v191
	v_add_f32_e32 v171, 1.0, v192
	v_add_f32_e32 v173, 1.0, v185
	v_add_f32_e32 v185, 1.0, v186
	v_add_f32_e32 v186, 1.0, v187
	v_add_f32_e32 v187, 1.0, v188
	v_exp_f32_e32 v188, v166
	v_exp_f32_e32 v189, v167
	v_exp_f32_e32 v190, v168
	v_exp_f32_e32 v191, v172
	v_exp_f32_e32 v192, v206
	v_exp_f32_e32 v206, v207
	v_exp_f32_e32 v207, v208
	v_exp_f32_e32 v208, v209
	v_rcp_f32_e32 v166, v41
	v_rcp_f32_e32 v167, v169
	v_rcp_f32_e32 v168, v170
	v_rcp_f32_e32 v169, v171
	v_rcp_f32_e32 v170, v173
	v_rcp_f32_e32 v171, v185
	v_rcp_f32_e32 v172, v186
	v_rcp_f32_e32 v173, v187
	v_add_f32_e32 v41, 1.0, v193
	v_add_f32_e32 v185, 1.0, v194
	v_add_f32_e32 v186, 1.0, v195
	v_add_f32_e32 v187, 1.0, v196
	v_add_f32_e32 v193, 1.0, v197
	v_add_f32_e32 v194, 1.0, v198
	v_add_f32_e32 v195, 1.0, v199
	v_add_f32_e32 v196, 1.0, v200
	v_pk_mul_f32 v[76:77], v[76:77], v[150:151]
	v_pk_mul_f32 v[78:79], v[78:79], v[152:153]
	v_pk_mul_f32 v[80:81], v[80:81], v[154:155]
	v_pk_mul_f32 v[82:83], v[82:83], v[156:157]
	v_rcp_f32_e32 v150, v41
; __device__ __forceinline__ unsigned pk2(float lo, float hi) { f32x2_c v = {lo, hi}; return __builtin_bit_cast(unsigned, __builtin_convertvector(v, bf16x2_c)); }
; __device__ __forceinline__ float bf2f(unsigned short h) { return __uint_as_float(((unsigned)h) << 16); }
; __device__ __forceinline__ float silu_f(float x) { return x * __builtin_amdgcn_rcpf(1.f + __expf(-x)); }
; __device__ __forceinline__ void p2a_conv(const Args& A, int G) {
;     ...
;             for (int e = 0; e < 8; ++e) { const float a = bs[e] + w[0][e] * bf2f((unsigned short)r0[e]) + w[1][e] * bf2f((unsigned short)r1[e]) + w[2][e] * bf2f((unsigned short)r2[e]) + w[3][e] * bf2f((unsigned short)r3[e]); o[e] = silu_f(a); }
;             v4u pw; pw.x = pk2(o[0], o[1]); pw.y = pk2(o[2], o[3]); pw.z = pk2(o[4], o[5]); pw.w = pk2(o[6], o[7]);
;             *(v4u*)(XC + (size_t)(m0 + i) * 2048 + ch) = pw; r0 = r1; r1 = r2; r2 = r3; } }
;     }
	v_rcp_f32_e32 v151, v185
	v_rcp_f32_e32 v152, v186
	v_rcp_f32_e32 v153, v187
	v_rcp_f32_e32 v154, v193
	v_rcp_f32_e32 v155, v194
	v_rcp_f32_e32 v156, v195
	v_rcp_f32_e32 v157, v196
	v_add_f32_e32 v41, 1.0, v174
	v_add_f32_e32 v174, 1.0, v175
	v_add_f32_e32 v175, 1.0, v176
	v_add_f32_e32 v176, 1.0, v202
	v_add_f32_e32 v185, 1.0, v203
	v_add_f32_e32 v186, 1.0, v204
	v_add_f32_e32 v187, 1.0, v205
	v_add_f32_e32 v193, 1.0, v201
	v_cvt_pk_bf16_f32 v76, v76, v77
	v_cvt_pk_bf16_f32 v77, v78, v79
	v_cvt_pk_bf16_f32 v78, v80, v81
	v_cvt_pk_bf16_f32 v79, v82, v83
	v_pk_mul_f32 v[80:81], v[84:85], v[142:143]
	v_pk_mul_f32 v[82:83], v[86:87], v[144:145]
	v_pk_mul_f32 v[84:85], v[88:89], v[146:147]
	v_pk_mul_f32 v[86:87], v[90:91], v[148:149]
	v_rcp_f32_e32 v88, v41
	v_rcp_f32_e32 v89, v174
	v_rcp_f32_e32 v90, v175
	v_rcp_f32_e32 v91, v176
	v_rcp_f32_e32 v142, v185
	v_rcp_f32_e32 v143, v186
	v_rcp_f32_e32 v144, v187
	v_rcp_f32_e32 v145, v193
	v_add_f32_e32 v41, 1.0, v177
	v_add_f32_e32 v146, 1.0, v178
	v_add_f32_e32 v147, 1.0, v179
	v_add_f32_e32 v148, 1.0, v180
	v_add_f32_e32 v149, 1.0, v181
	v_add_f32_e32 v174, 1.0, v182
	v_add_f32_e32 v175, 1.0, v183
	v_add_f32_e32 v176, 1.0, v184
	flat_store_dwordx4 v[74:75], v[76:79]
	v_cvt_pk_bf16_f32 v74, v80, v81
	v_cvt_pk_bf16_f32 v75, v82, v83
	v_cvt_pk_bf16_f32 v76, v84, v85
	v_cvt_pk_bf16_f32 v77, v86, v87
	v_pk_mul_f32 v[78:79], v[92:93], v[158:159]
	v_pk_mul_f32 v[80:81], v[94:95], v[160:161]
	v_pk_mul_f32 v[82:83], v[96:97], v[162:163]
	v_pk_mul_f32 v[84:85], v[98:99], v[164:165]
	v_rcp_f32_e32 v86, v41
	v_rcp_f32_e32 v87, v146
	v_rcp_f32_e32 v92, v147
	v_rcp_f32_e32 v93, v148
	v_rcp_f32_e32 v94, v149
	v_rcp_f32_e32 v95, v174
	v_rcp_f32_e32 v96, v175
	v_rcp_f32_e32 v97, v176
	v_add_f32_e32 v41, 1.0, v188
	v_add_f32_e32 v98, 1.0, v189
	v_add_f32_e32 v99, 1.0, v190
	v_add_f32_e32 v146, 1.0, v191
	v_add_f32_e32 v147, 1.0, v192
	v_add_f32_e32 v148, 1.0, v206
	v_add_f32_e32 v149, 1.0, v207
	v_add_f32_e32 v158, 1.0, v208
	flat_store_dwordx4 v[72:73], v[74:77]
	v_cvt_pk_bf16_f32 v72, v78, v79
	v_cvt_pk_bf16_f32 v73, v80, v81
	v_cvt_pk_bf16_f32 v74, v82, v83
	v_cvt_pk_bf16_f32 v75, v84, v85
	v_pk_mul_f32 v[76:77], v[100:101], v[166:167]
	v_pk_mul_f32 v[78:79], v[102:103], v[168:169]
	v_pk_mul_f32 v[80:81], v[104:105], v[170:171]
	v_pk_mul_f32 v[82:83], v[106:107], v[172:173]
	v_rcp_f32_e32 v84, v41
	v_rcp_f32_e32 v85, v98
	v_rcp_f32_e32 v98, v99
	v_rcp_f32_e32 v99, v146
	v_rcp_f32_e32 v100, v147
	v_rcp_f32_e32 v101, v148
	v_rcp_f32_e32 v102, v149
	v_rcp_f32_e32 v103, v158
	flat_store_dwordx4 v[70:71], v[72:75]
	v_cvt_pk_bf16_f32 v70, v76, v77
	v_cvt_pk_bf16_f32 v71, v78, v79
	v_cvt_pk_bf16_f32 v72, v80, v81
	v_cvt_pk_bf16_f32 v73, v82, v83
	v_pk_mul_f32 v[74:75], v[108:109], v[150:151]
	v_pk_mul_f32 v[76:77], v[110:111], v[152:153]
	v_pk_mul_f32 v[78:79], v[112:113], v[154:155]
	v_pk_mul_f32 v[80:81], v[114:115], v[156:157]
	flat_store_dwordx4 v[68:69], v[70:73]
	v_cvt_pk_bf16_f32 v68, v74, v75
	v_cvt_pk_bf16_f32 v69, v76, v77
	v_cvt_pk_bf16_f32 v70, v78, v79
	v_cvt_pk_bf16_f32 v71, v80, v81
	v_pk_mul_f32 v[72:73], v[116:117], v[88:89]
	v_pk_mul_f32 v[74:75], v[118:119], v[90:91]
	v_pk_mul_f32 v[76:77], v[120:121], v[142:143]
	v_pk_mul_f32 v[78:79], v[122:123], v[144:145]
	flat_store_dwordx4 v[66:67], v[68:71]
	v_cvt_pk_bf16_f32 v66, v72, v73
	v_cvt_pk_bf16_f32 v67, v74, v75
	v_cvt_pk_bf16_f32 v68, v76, v77
	v_cvt_pk_bf16_f32 v69, v78, v79
	v_pk_mul_f32 v[70:71], v[126:127], v[86:87]
	v_pk_mul_f32 v[72:73], v[128:129], v[92:93]
	v_pk_mul_f32 v[74:75], v[132:133], v[94:95]
	v_pk_mul_f32 v[76:77], v[136:137], v[96:97]
	flat_store_dwordx4 v[64:65], v[66:69]
	v_cvt_pk_bf16_f32 v64, v70, v71
	v_cvt_pk_bf16_f32 v65, v72, v73
	v_cvt_pk_bf16_f32 v66, v74, v75
	v_cvt_pk_bf16_f32 v67, v76, v77
	v_pk_mul_f32 v[68:69], v[130:131], v[84:85]
	v_pk_mul_f32 v[70:71], v[138:139], v[98:99]
	v_pk_mul_f32 v[72:73], v[140:141], v[100:101]
	v_pk_mul_f32 v[74:75], v[134:135], v[102:103]
	flat_store_dwordx4 v[62:63], v[64:67]
	v_cvt_pk_bf16_f32 v62, v68, v69
	v_cvt_pk_bf16_f32 v63, v70, v71
	v_cvt_pk_bf16_f32 v64, v72, v73
	v_cvt_pk_bf16_f32 v65, v74, v75
	flat_store_dwordx4 v[60:61], v[62:65]
	s_cbranch_scc0 .LBB0_603
	s_add_i32 s3, s3, s38
	s_cmpk_gt_i32 s3, 0xff
	v_add_u32_e32 v125, s0, v125
	s_cbranch_scc0 .LBB0_600
